# scan prep waves: Dm1 = D/dec replaced by the exclusive prefix product (D shifted one lane by DPP, 1.0 in lane 0): 4 IEEE divisions per thread per chunk removed
# speedup vs baseline: 1.0012x; 1.0012x over previous
.LBB0_588:
	s_or_b64 exec, exec, s[16:17]
	s_waitcnt vmcnt(18)
	v_mfma_f32_16x16x32_bf16 v[126:129], v[30:33], v[62:65], 0
	s_waitcnt vmcnt(14)
	v_lshlrev_b32_e32 v116, 16, v114
	s_waitcnt vmcnt(11)
	v_lshlrev_b32_e32 v174, 16, v121
	v_and_b32_e32 v175, 0xffff0000, v121
	v_mfma_f32_16x16x32_bf16 v[126:129], v[26:29], v[50:53], v[126:129]
	v_lshlrev_b32_e32 v50, 16, v124
	v_and_b32_e32 v51, 0xffff0000, v124
	v_lshlrev_b32_e32 v52, 16, v125
	v_mfma_f32_16x16x32_bf16 v[170:173], v[22:25], v[58:61], 0
	v_and_b32_e32 v53, 0xffff0000, v125
	s_nop 2
	v_add_f32_e32 v60, v14, v126
	v_lshlrev_b32_e32 v58, 16, v122
	v_mfma_f32_16x16x32_bf16 v[170:173], v[18:21], v[54:57], v[170:173]
	v_mul_f32_e64 v54, |v60|, s74
	v_exp_f32_e32 v56, v54
	v_and_b32_e32 v59, 0xffff0000, v122
	v_lshlrev_b32_e32 v54, 16, v123
	v_and_b32_e32 v55, 0xffff0000, v123
	v_add_f32_e32 v56, 1.0, v56
	v_cmp_gt_f32_e32 vcc, s75, v56
	v_lshlrev_b32_e32 v122, 16, v120
	v_and_b32_e32 v123, 0xffff0000, v120
	v_cndmask_b32_e64 v57, 0, 32, vcc
	v_ldexp_f32 v56, v56, v57
	v_log_f32_e32 v56, v56
	v_max_f32_e64 v57, -v60, 0
	v_and_b32_e32 v114, 0xffff0000, v114
	v_lshlrev_b32_e32 v64, 16, v115
	v_mul_f32_e32 v60, 0x3f317217, v56
	v_fma_f32 v60, v56, s76, -v60
	v_fmac_f32_e32 v60, 0x3377d1cf, v56
	v_fmac_f32_e32 v60, 0x3f317217, v56
	v_cmp_lt_f32_e64 s[16:17], |v56|, s77
	v_and_b32_e32 v62, 0xffff0000, v115
	v_pk_mul_f32 v[174:175], v[8:9], v[174:175]
	v_cndmask_b32_e64 v56, v56, v60, s[16:17]
	v_cndmask_b32_e32 v60, 0, v164, vcc
	v_sub_f32_e32 v56, v56, v60
	v_add_f32_e32 v56, v57, v56
	v_sub_f32_e32 v56, -0.5, v56
	v_add_f32_e32 v57, v10, v170
	v_mul_f32_e32 v56, 0x3fb8aa3b, v56
	v_mul_f32_e32 v57, 0xbfb8aa3b, v57
	v_exp_f32_e32 v56, v56
	v_exp_f32_e32 v57, v57
	v_pk_mul_f32 v[122:123], v[6:7], v[122:123]
	s_add_i32 s88, s83, 2
	v_mul_f32_e32 v60, 0xbfb8aa3b, v56
	v_add_f32_e32 v56, 1.0, v57
	v_add_f32_e32 v57, v15, v127
	v_mul_f32_e64 v61, |v57|, s74
	v_exp_f32_e32 v63, v61
	v_rcp_f32_e32 v56, v56
	v_exp_f32_e32 v124, v60
	v_max_f32_e64 v57, -v57, 0
	v_add_f32_e32 v63, 1.0, v63
	v_cmp_gt_f32_e32 vcc, s75, v63
	v_add_f32_e32 v117, -1.0, v56
	v_pk_mul_f32 v[60:61], v[94:95], v[116:117]
	v_cndmask_b32_e64 v65, 0, 32, vcc
	v_ldexp_f32 v63, v63, v65
	v_log_f32_e32 v63, v63
	s_waitcnt vmcnt(10)
	v_pk_mul_f32 v[60:61], v[80:81], v[60:61]
	v_pk_fma_f32 v[120:121], v[94:95], v[116:117], s[2:3]
	ds_bpermute_b32 v170, v168, v124
	v_mul_f32_e32 v61, 0x3f317217, v63
	v_fma_f32 v61, v63, s76, -v61
	v_fmac_f32_e32 v61, 0x3377d1cf, v63
	v_fmac_f32_e32 v61, 0x3f317217, v63
	v_cmp_lt_f32_e64 s[16:17], |v63|, s77
	s_waitcnt vmcnt(9)
	v_pk_mul_f32 v[122:123], v[118:119], v[122:123] op_sel_hi:[0,1]
	s_and_b32 s88, s88, 1
	v_cndmask_b32_e64 v61, v63, v61, s[16:17]
	v_cndmask_b32_e32 v63, 0, v164, vcc
	v_sub_f32_e32 v61, v61, v63
	v_add_f32_e32 v57, v57, v61
	v_sub_f32_e32 v57, -0.5, v57
	v_mul_f32_e32 v57, 0x3fb8aa3b, v57
	v_exp_f32_e32 v57, v57
	v_add_f32_e32 v61, v11, v171
	v_mul_f32_e32 v61, 0xbfb8aa3b, v61
	v_exp_f32_e32 v61, v61
	v_mul_f32_e32 v57, 0xbfb8aa3b, v57
	v_exp_f32_e32 v125, v57
	v_add_f32_e32 v57, v16, v128
	v_mul_f32_e64 v63, |v57|, s74
	v_exp_f32_e32 v63, v63
	v_max_f32_e64 v57, -v57, 0
	v_add_f32_e32 v61, 1.0, v61
	v_rcp_f32_e32 v120, v61
	v_add_f32_e32 v63, 1.0, v63
	v_cmp_gt_f32_e32 vcc, s75, v63
	ds_bpermute_b32 v171, v168, v125
	v_add_f32_e32 v115, -1.0, v120
	v_cndmask_b32_e64 v65, 0, 32, vcc
	v_ldexp_f32 v63, v63, v65
	v_log_f32_e32 v63, v63
	v_pk_mul_f32 v[126:127], v[92:93], v[114:115]
	v_pk_fma_f32 v[130:131], v[92:93], v[114:115], s[2:3]
	v_add_f32_e32 v115, v12, v172
	v_mul_f32_e32 v65, 0x3f317217, v63
	v_fma_f32 v65, v63, s76, -v65
	v_fmac_f32_e32 v65, 0x3377d1cf, v63
	v_fmac_f32_e32 v65, 0x3f317217, v63
	v_cmp_lt_f32_e64 s[16:17], |v63|, s77
	v_mul_f32_e32 v115, 0xbfb8aa3b, v115
	v_exp_f32_e32 v115, v115
	v_cndmask_b32_e64 v63, v63, v65, s[16:17]
	v_cndmask_b32_e32 v65, 0, v164, vcc
	v_sub_f32_e32 v63, v63, v65
	v_add_f32_e32 v57, v57, v63
	v_add_f32_e32 v63, v17, v129
	v_mul_f32_e64 v65, |v63|, s74
	v_exp_f32_e32 v65, v65
	v_add_f32_e32 v115, 1.0, v115
	v_rcp_f32_e32 v128, v115
	v_max_f32_e64 v63, -v63, 0
	v_add_f32_e32 v65, 1.0, v65
	v_cmp_gt_f32_e32 vcc, s75, v65
	v_sub_f32_e32 v57, -0.5, v57
	v_mul_f32_e32 v57, 0x3fb8aa3b, v57
	v_cndmask_b32_e64 v117, 0, 32, vcc
	v_ldexp_f32 v65, v65, v117
	v_log_f32_e32 v65, v65
	v_exp_f32_e32 v57, v57
	s_waitcnt lgkmcnt(0)
	v_pk_mul_f32 v[170:171], v[124:125], v[170:171]
	v_pk_mul_f32 v[126:127], v[80:81], v[126:127]
	v_mul_f32_e32 v115, 0x3f317217, v65
	v_fma_f32 v115, v65, s76, -v115
	v_fmac_f32_e32 v115, 0x3377d1cf, v65
	v_fmac_f32_e32 v115, 0x3f317217, v65
	v_cmp_lt_f32_e64 s[16:17], |v65|, s77
	v_cndmask_b32_e64 v171, v171, v125, s[4:5]
	v_cndmask_b32_e64 v170, v170, v124, s[4:5]
	v_cndmask_b32_e64 v65, v65, v115, s[16:17]
	v_cndmask_b32_e32 v115, 0, v164, vcc
	v_sub_f32_e32 v65, v65, v115
	v_add_f32_e32 v63, v63, v65
	v_sub_f32_e32 v63, -0.5, v63
	v_mul_f32_e32 v63, 0x3fb8aa3b, v63
	v_exp_f32_e32 v63, v63
	ds_bpermute_b32 v182, v167, v170
	ds_bpermute_b32 v183, v167, v171
	v_mul_f32_e32 v57, 0xbfb8aa3b, v57
	v_exp_f32_e32 v176, v57
	v_mul_f32_e32 v57, 0xbfb8aa3b, v63
	v_exp_f32_e32 v177, v57
	v_add_f32_e32 v57, v13, v173
	s_waitcnt lgkmcnt(0)
	v_pk_mul_f32 v[172:173], v[170:171], v[182:183]
	ds_bpermute_b32 v178, v168, v176
	v_cndmask_b32_e64 v171, v173, v171, s[6:7]
	v_cndmask_b32_e64 v170, v172, v170, s[6:7]
	ds_bpermute_b32 v179, v168, v177
	ds_bpermute_b32 v172, v166, v170
	ds_bpermute_b32 v173, v166, v171
	v_mul_f32_e32 v57, 0xbfb8aa3b, v57
	v_exp_f32_e32 v57, v57
	s_waitcnt lgkmcnt(2)
	v_pk_mul_f32 v[178:179], v[176:177], v[178:179]
	v_add_f32_e32 v65, -1.0, v128
	s_waitcnt lgkmcnt(0)
	v_pk_mul_f32 v[172:173], v[170:171], v[172:173]
	v_cndmask_b32_e64 v179, v179, v177, s[4:5]
	v_cndmask_b32_e64 v178, v178, v176, s[4:5]
	v_cndmask_b32_e64 v171, v173, v171, s[8:9]
	v_cndmask_b32_e64 v170, v172, v170, s[8:9]
	ds_bpermute_b32 v184, v167, v178
	ds_bpermute_b32 v185, v167, v179
	ds_bpermute_b32 v172, v165, v170
	ds_bpermute_b32 v173, v165, v171
	v_pk_fma_f32 v[180:181], v[90:91], v[64:65], s[2:3]
	v_add_f32_e32 v57, 1.0, v57
	s_waitcnt lgkmcnt(2)
	v_pk_mul_f32 v[182:183], v[178:179], v[184:185]
	v_pk_mul_f32 v[184:185], v[118:119], v[174:175] op_sel_hi:[0,1]
	s_waitcnt lgkmcnt(0)
	v_pk_mul_f32 v[174:175], v[170:171], v[172:173]
	v_rcp_f32_e32 v180, v57
	v_cndmask_b32_e64 v170, v174, v170, s[10:11]
	v_div_scale_f32 v57, s[16:17], v170, v170, 1.0
	v_mov_b32_e32 v127, v131
	v_pk_mul_f32 v[130:131], v[90:91], v[64:65]
	v_cndmask_b32_e64 v179, v183, v179, s[6:7]
	v_cndmask_b32_e64 v178, v182, v178, s[6:7]
	v_rcp_f32_e32 v65, v57
	ds_bpermute_b32 v182, v166, v178
	ds_bpermute_b32 v183, v166, v179
	v_cndmask_b32_e64 v171, v175, v171, s[10:11]
	v_fma_f32 v115, -v57, v65, 1.0
	v_fmac_f32_e32 v65, v115, v65
	v_div_scale_f32 v115, vcc, 1.0, v170, 1.0
	s_waitcnt lgkmcnt(0)
	v_pk_mul_f32 v[182:183], v[178:179], v[182:183]
	v_mul_f32_e32 v117, v115, v65
	v_cndmask_b32_e64 v179, v183, v179, s[8:9]
	v_cndmask_b32_e64 v178, v182, v178, s[8:9]
	v_fma_f32 v118, -v57, v117, v115
	ds_bpermute_b32 v182, v165, v178
	ds_bpermute_b32 v183, v165, v179
	v_fmac_f32_e32 v117, v118, v65
	v_fma_f32 v57, -v57, v117, v115
	s_waitcnt lgkmcnt(0)
	v_pk_mul_f32 v[172:173], v[178:179], v[182:183]
	v_div_fmas_f32 v57, v57, v65, v117
	v_cndmask_b32_e64 v172, v172, v178, s[10:11]
	v_div_fixup_f32 v178, v57, v170, 1.0
	v_div_scale_f32 v115, s[16:17], v171, v171, 1.0
	v_rcp_f32_e32 v117, v115
	v_mov_b32_e32 v61, v121
	v_cndmask_b32_e64 v173, v173, v179, s[10:11]
	v_fma_f32 v65, -v115, v117, 1.0
	v_fmac_f32_e32 v117, v65, v117
	v_div_scale_f32 v65, vcc, 1.0, v171, 1.0
	v_mul_f32_e32 v118, v65, v117
	v_fma_f32 v121, -v115, v118, v65
	v_fmac_f32_e32 v118, v121, v117
	v_fma_f32 v65, -v115, v118, v65
	v_div_fmas_f32 v65, v65, v117, v118
	v_div_fixup_f32 v179, v65, v171, 1.0
	v_mov_b32_e32 v57, 1.0
	v_mov_b32_dpp v57, v170 row_shr:1 row_mask:0xf bank_mask:0xf
	v_div_scale_f32 v115, s[16:17], v172, v172, 1.0
	v_rcp_f32_e32 v118, v115
	v_mov_b32_e32 v65, 1.0
	v_mov_b32_dpp v65, v171 row_shr:1 row_mask:0xf bank_mask:0xf
	v_pk_mul_f32 v[124:125], v[122:123], v[124:125]
	v_fma_f32 v117, -v115, v118, 1.0
	v_fmac_f32_e32 v118, v117, v118
	v_div_scale_f32 v117, vcc, 1.0, v172, 1.0
	v_mul_f32_e32 v121, v117, v118
	v_fma_f32 v129, -v115, v121, v117
	v_fmac_f32_e32 v121, v129, v118
	v_fma_f32 v115, -v115, v121, v117
	v_div_fmas_f32 v115, v115, v118, v121
	v_div_fixup_f32 v182, v115, v172, 1.0
	v_xor_b32_e32 v187, 0x80000000, v65
	v_div_scale_f32 v117, s[16:17], v173, v173, 1.0
	v_rcp_f32_e32 v121, v117
	v_mov_b32_e32 v115, 1.0
	v_mov_b32_dpp v115, v172 row_shr:1 row_mask:0xf bank_mask:0xf
	v_xor_b32_e32 v186, 0x80000000, v57
	v_fma_f32 v118, -v117, v121, 1.0
	v_fmac_f32_e32 v121, v118, v121
	v_div_scale_f32 v118, vcc, 1.0, v173, 1.0
	v_mul_f32_e32 v129, v118, v121
	v_fma_f32 v174, -v117, v129, v118
	v_fmac_f32_e32 v129, v174, v121
	v_fma_f32 v117, -v117, v129, v118
	v_div_fmas_f32 v117, v117, v121, v129
	v_div_fixup_f32 v183, v117, v173, 1.0
	s_mul_i32 s16, s88, 0x6000
	v_mov_b32_e32 v117, 1.0
	v_mov_b32_dpp v117, v173 row_shr:1 row_mask:0xf bank_mask:0xf
	v_pk_mul_f32 v[174:175], v[184:185], v[176:177]
	v_add_u32_e32 v118, s16, v143
	v_xor_b32_e32 v177, 0x80000000, v117
	v_xor_b32_e32 v176, 0x80000000, v115
	v_mov_b32_e32 v57, v116
	v_pk_mul_f32 v[130:131], v[80:81], v[130:131]
	ds_write_b128 v118, v[170:173]
	v_pk_mul_f32 v[176:177], v[174:175], v[176:177]
	v_pk_mul_f32 v[174:175], v[124:125], v[186:187]
	v_pk_mul_f32 v[172:173], v[172:173], v[54:55]
	v_pk_mul_f32 v[170:171], v[170:171], v[58:59]
	v_pk_mul_f32 v[56:57], v[60:61], v[56:57]
	v_mov_b32_e32 v121, v114
	v_mov_b32_e32 v131, v181
	ds_write_b128 v118, v[174:177] offset:4096
	ds_write_b128 v118, v[170:173] offset:16384
	ds_write_b128 v118, v[50:53] offset:20480
	v_mul_f32_e32 v50, v57, v58
	v_pk_mul_f32 v[60:61], v[126:127], v[120:121]
	v_mov_b32_e32 v129, v64
	v_fma_f32 v116, v2, v50, 0
	v_mul_f32_e32 v50, v61, v59
	v_pk_mul_f32 v[58:59], v[130:131], v[128:129]
	v_add_f32_e32 v63, -1.0, v180
	v_fmac_f32_e32 v116, v3, v50
	v_mul_f32_e32 v50, v59, v54
	v_fmac_f32_e32 v116, v4, v50
	v_pk_mul_f32 v[50:51], v[86:87], v[62:63]
	v_pk_fma_f32 v[52:53], v[86:87], v[62:63], s[2:3]
	v_pk_mul_f32 v[50:51], v[80:81], v[50:51]
	v_mov_b32_e32 v181, v62
	v_mov_b32_e32 v51, v53
	v_pk_mul_f32 v[62:63], v[50:51], v[180:181]
	s_nop 0
	v_mul_f32_e32 v50, v63, v55
	v_fmac_f32_e32 v116, v5, v50
	v_pk_fma_f32 v[50:51], v[122:123], v[56:57], 0 op_sel_hi:[0,1,0]
	v_pk_fma_f32 v[50:51], v[122:123], v[60:61], v[50:51] op_sel:[1,0,0]
	ds_bpermute_b32 v54, v83, v116
	v_pk_fma_f32 v[50:51], v[184:185], v[58:59], v[50:51] op_sel_hi:[0,1,1]
	v_pk_fma_f32 v[64:65], v[184:185], v[62:63], v[50:51] op_sel:[1,0,0]
	ds_bpermute_b32 v114, v83, v64
	ds_bpermute_b32 v115, v83, v65
	v_mov_b32_e32 v50, v58
	v_mov_b32_e32 v51, v62
	v_pk_mul_f32 v[52:53], v[50:51], v[182:183]
	v_mov_b32_e32 v50, v56
	v_mov_b32_e32 v51, v60
	v_pk_mul_f32 v[50:51], v[50:51], v[178:179]
	ds_write_b128 v118, v[50:53] offset:8192
	s_waitcnt lgkmcnt(3)
	v_add_f32_e32 v54, v116, v54
	s_waitcnt lgkmcnt(1)
	v_pk_add_f32 v[50:51], v[64:65], v[114:115]
	ds_bpermute_b32 v55, v79, v54
	ds_bpermute_b32 v52, v79, v50
	ds_bpermute_b32 v53, v79, v51
	v_mov_b32_e32 v62, v59
	v_mov_b32_e32 v60, v57
	v_pk_mul_f32 v[58:59], v[62:63], v[182:183]
	v_pk_mul_f32 v[56:57], v[60:61], v[178:179]
	ds_write_b128 v118, v[56:59] offset:12288
	s_and_saveexec_b64 s[16:17], s[14:15]
	s_cbranch_execz .LBB0_590
	s_add_i32 s89, s82, 0x80
	s_and_b32 s89, s89, 0xc0
	s_waitcnt lgkmcnt(3)
	v_add_f32_e32 v54, v54, v55
	v_lshl_add_u32 v55, s89, 2, v144
	ds_write_b32 v55, v54
	v_lshl_add_u32 v54, s88, 9, v145
	s_waitcnt lgkmcnt(2)
	v_pk_add_f32 v[50:51], v[50:51], v[52:53]
	ds_write_b64 v54, v[50:51]
